# prompt attention: K tile staged through LDS with full-line loads shared by the 4 waves of a kv head (2 barriers per item)
# speedup vs baseline: 1.0081x; 1.0081x over previous
; __device__ __forceinline__ void attn_prompt_wave(const Params& P, int l, int qt, int tid_in) {
;     ...
;     const int q0 = qt * 32, key0 = q0 - 128;
;     bf16x8 qf[4];
; #pragma unroll
;     for (int kk = 0; kk < 4; ++kk) qf[kk] = *(const bf16x8*)(Q + (size_t)(q0 + l32) * 512 + head * 64 + kk * 16 + h * 8);
;     bf16x8 kf[5][4];
; #pragma unroll
;     for (int kb = 0; kb < 5; ++kb) {
;         int krow_ = key0 + kb * 32 + l32; krow_ = krow_ < 0 ? 0 : krow_;
;         const bf16* kp = KB + (size_t)krow_ * 128 + kvh * 64 + h * 8;
; #pragma unroll
;         for (int kk = 0; kk < 4; ++kk) kf[kb][kk] = *(const bf16x8*)(kp + kk * 16);
;     }
.LBB0_1019:
	s_and_b64 vcc, exec, s[0:1]
	s_cbranch_vccz .LBB0_953
	s_lshl_b32 s0, s14, 5
	v_readlane_b32 s2, v254, 0
	v_readlane_b32 s3, v254, 1
	v_and_b32_e32 v72, 7, v216
	v_bfe_u32 v73, v216, 3, 5
	v_ashrrev_i32_e32 v74, 8, v216
	v_lshlrev_b32_e32 v75, 4, v72
	s_addk_i32 s0, 0xff80
	v_lshl_or_b32 v75, v74, 7, v75
	v_add_u32_e32 v64, s0, v73
	v_mul_u32_u24_e32 v68, 0x90, v73
	v_mul_u32_u24_e32 v74, 0x5a00, v74
	v_lshl_add_u32 v68, v72, 4, v68
	v_add_u32_e32 v68, v68, v74
	v_max_i32_e32 v65, 0, v64
	v_lshl_add_u32 v65, v65, 8, v75
	global_load_dwordx4 v[28:31], v65, s[2:3]
	v_add_u32_e32 v65, 32, v64
	v_max_i32_e32 v65, 0, v65
	v_lshl_add_u32 v65, v65, 8, v75
	global_load_dwordx4 v[24:27], v65, s[2:3]
	v_add_u32_e32 v65, 64, v64
	v_max_i32_e32 v65, 0, v65
	v_lshl_add_u32 v65, v65, 8, v75
	global_load_dwordx4 v[16:19], v65, s[2:3]
	v_add_u32_e32 v65, 96, v64
	v_max_i32_e32 v65, 0, v65
	v_lshl_add_u32 v65, v65, 8, v75
	global_load_dwordx4 v[20:23], v65, s[2:3]
	v_add_u32_e32 v65, 128, v64
	v_max_i32_e32 v65, 0, v65
	v_lshl_add_u32 v65, v65, 8, v75
	global_load_dwordx4 v[76:79], v65, s[2:3]
	v_mov_b32_e32 v10, v216
	s_lshl_b32 s0, s14, 5
	v_and_b32_e32 v11, 31, v10
	v_ashrrev_i32_e32 v13, 8, v10
	v_or_b32_e32 v182, s0, v11
	v_lshlrev_b32_e32 v0, 6, v13
	v_readlane_b32 s2, v254, 0
	v_bfe_u32 v12, v10, 5, 1
	v_ashrrev_i32_e32 v183, 31, v182
	v_readlane_b32 s36, v252, 1
	s_add_i32 s1, s0, 0xffffff80
	v_ashrrev_i32_e32 v1, 31, v0
	v_readlane_b32 s3, v254, 1
	v_lshlrev_b64 v[178:179], 10, v[182:183]
	v_readlane_b32 s38, v252, 3
	v_readlane_b32 s39, v252, 4
	v_lshlrev_b32_e32 v80, 4, v12
	v_lshl_add_u64 v[0:1], v[0:1], 1, s[2:3]
	s_cmp_lt_i32 s14, 4
	v_lshl_add_u64 v[4:5], s[38:39], 0, v[178:179]
	v_lshl_add_u64 v[6:7], v[0:1], 0, v[80:81]
	v_or_b32_e32 v0, s1, v11
	s_cselect_b64 s[38:39], -1, 0
	v_cndmask_b32_e64 v0, v0, 0, s[38:39]
	v_ashrrev_i32_e32 v1, 31, v0
	v_lshlrev_b64 v[0:1], 8, v[0:1]
	v_lshl_add_u64 v[8:9], v[6:7], 0, v[0:1]
	v_and_b32_e32 v180, 0xffffffc0, v10
	v_ashrrev_i32_e32 v181, 31, v180
	v_lshl_add_u64 v[4:5], v[180:181], 1, v[4:5]
	v_lshl_add_u64 v[4:5], v[4:5], 0, v[80:81]
	global_load_dwordx4 v[32:35], v[4:5], off
	global_load_dwordx4 v[90:93], v[4:5], off offset:32
	global_load_dwordx4 v[166:169], v[4:5], off offset:64
	global_load_dwordx4 v[162:165], v[4:5], off offset:96
	s_add_i32 s17, s0, 0xffffffa0
	v_readlane_b32 s37, v252, 2
	s_cmp_lt_i32 s14, 3
	v_or_b32_e32 v4, s17, v11
	s_cselect_b64 s[36:37], -1, 0
	v_cndmask_b32_e64 v4, v4, 0, s[36:37]
	v_ashrrev_i32_e32 v5, 31, v4
	v_lshlrev_b64 v[4:5], 8, v[4:5]
	v_lshl_add_u64 v[4:5], v[6:7], 0, v[4:5]
	s_sub_i32 s16, s0, 64
	s_cmp_lt_i32 s14, 2
	v_or_b32_e32 v4, s16, v11
	s_cselect_b64 s[8:9], -1, 0
	v_cndmask_b32_e64 v4, v4, 0, s[8:9]
	v_ashrrev_i32_e32 v5, 31, v4
	v_lshlrev_b64 v[4:5], 8, v[4:5]
	v_lshl_add_u64 v[4:5], v[6:7], 0, v[4:5]
	s_sub_i32 s15, s0, 32
	s_cmp_lt_i32 s14, 1
	v_or_b32_e32 v4, s15, v11
	s_cselect_b64 s[4:5], -1, 0
	v_cndmask_b32_e64 v4, v4, 0, s[4:5]
	v_ashrrev_i32_e32 v5, 31, v4
	v_lshlrev_b64 v[4:5], 8, v[4:5]
	s_cmp_lt_i32 s14, 0
	v_lshl_add_u64 v[4:5], v[6:7], 0, v[4:5]
	s_cselect_b64 s[2:3], -1, 0
	v_cndmask_b32_e64 v4, v182, 0, s[2:3]
	v_ashrrev_i32_e32 v5, 31, v4
	v_lshlrev_b64 v[4:5], 8, v[4:5]
	v_lshl_add_u64 v[4:5], v[6:7], 0, v[4:5]
	v_lshlrev_b32_e32 v80, 2, v12
	v_mul_i32_i24_e32 v4, 0x43000, v13
	v_readlane_b32 s18, v254, 2
	v_or_b32_e32 v183, s1, v80
	v_mul_hi_i32_i24_e32 v5, 0x43000, v13
	v_or_b32_e32 v4, v4, v11
	v_readlane_b32 s19, v254, 3
	v_ashrrev_i32_e32 v104, 2, v183
	v_or_b32_e32 v6, 2, v104
	v_lshl_add_u64 v[184:185], v[4:5], 3, s[18:19]
	v_cndmask_b32_e64 v4, v104, 0, s[38:39]
	v_ashrrev_i32_e32 v5, 31, v4
	v_cndmask_b32_e64 v6, v6, 0, s[38:39]
	v_lshlrev_b64 v[4:5], 9, v[4:5]
	v_ashrrev_i32_e32 v7, 31, v6
	v_lshlrev_b64 v[6:7], 9, v[6:7]
	v_lshl_add_u64 v[4:5], v[184:185], 0, v[4:5]
	v_lshl_add_u64 v[6:7], v[184:185], 0, v[6:7]
	global_load_dwordx2 v[86:87], v[4:5], off
	global_load_dwordx2 v[88:89], v[6:7], off
	global_load_dwordx2 v[84:85], v[6:7], off offset:256
	global_load_dwordx2 v[82:83], v[4:5], off offset:256
	v_or_b32_e32 v4, 4, v104
	v_ashrrev_i32_e32 v190, 6, v10
	v_cndmask_b32_e64 v102, v4, 0, s[38:39]
	v_or_b32_e32 v104, 6, v104
	v_cndmask_b32_e64 v104, v104, 0, s[38:39]
	s_waitcnt vmcnt(8)
	ds_write_b128 v68, v[28:31]
	ds_write_b128 v68, v[24:27] offset:4608
	ds_write_b128 v68, v[16:19] offset:9216
	ds_write_b128 v68, v[20:23] offset:13824
	ds_write_b128 v68, v[76:79] offset:18432
	v_and_b32_e32 v170, 31, v216
	v_bfe_u32 v171, v216, 5, 1
	v_mul_u32_u24_e32 v170, 0x90, v170
	v_ashrrev_i32_e32 v172, 8, v216
	v_lshl_add_u32 v170, v171, 4, v170
	v_mul_u32_u24_e32 v172, 0x5a00, v172
	s_nop 0
	v_add_u32_e32 v170, v170, v172
	s_waitcnt lgkmcnt(0)
	s_barrier
	ds_read_b128 v[0:3], v170
	ds_read_b128 v[28:31], v170 offset:32
	ds_read_b128 v[24:27], v170 offset:64
	ds_read_b128 v[16:19], v170 offset:96
	ds_read_b128 v[20:23], v170 offset:4608
	ds_read_b128 v[76:79], v170 offset:4640
	ds_read_b128 v[72:75], v170 offset:4672
	ds_read_b128 v[64:67], v170 offset:4704
	ds_read_b128 v[68:71], v170 offset:9216
	ds_read_b128 v[60:63], v170 offset:9248
	ds_read_b128 v[56:59], v170 offset:9280
	ds_read_b128 v[48:51], v170 offset:9312
	ds_read_b128 v[52:55], v170 offset:13824
	ds_read_b128 v[98:101], v170 offset:13856
	ds_read_b128 v[44:47], v170 offset:13888
	ds_read_b128 v[36:39], v170 offset:13920
	ds_read_b128 v[40:43], v170 offset:18432
	ds_read_b128 v[94:97], v170 offset:18464
	ds_read_b128 v[174:177], v170 offset:18496
	ds_read_b128 v[170:173], v170 offset:18528
	s_waitcnt lgkmcnt(0)
	s_barrier
; #define MFMA32(a, b, c) __builtin_amdgcn_mfma_f32_32x32x16_bf16((a), (b), (c), 0, 0, 0)
; __device__ __forceinline__ void attn_prompt_wave(const Params& P, int l, int qt, int tid_in) {
;     ...
;     u32x2 vfa[5][2][2], vfb[5][2][2];
; #pragma unroll
;     for (int kb = 0; kb < 5; ++kb)
; #pragma unroll
;         for (int s = 0; s < 2; ++s) {
;             int k0 = key0 + kb * 32 + 16 * s + 4 * h, k1 = k0 + 8; k0 = k0 < 0 ? 0 : k0; k1 = k1 < 0 ? 0 : k1;
; #pragma unroll
;             for (int db = 0; db < 2; ++db) {
;                 const bf16* vp = VT + ((size_t)kvh * (MP / 4) * 64 + db * 32 + l32) * 4;
;                 vfa[kb][s][db] = *(const u32x2*)(vp + (size_t)(k0 >> 2) * 256); vfb[kb][s][db] = *(const u32x2*)(vp + (size_t)(k1 >> 2) * 256);
;             }
;         }
;     f32x16 st[5];
; #pragma unroll
;     for (int kb = 0; kb < 5; ++kb) {
; #pragma unroll
;         for (int i = 0; i < 16; ++i) st[kb][i] = 0.f;
; #pragma unroll
;         for (int kk = 0; kk < 4; ++kk) st[kb] = MFMA32(kf[kb][kk], qf[kk], st[kb]);
;     }
	s_waitcnt vmcnt(7)
	v_mfma_f32_32x32x16_bf16 v[0:15], v[0:3], v[32:35], 0
	v_ashrrev_i32_e32 v103, 31, v102
	v_ashrrev_i32_e32 v105, 31, v104
	v_lshlrev_b64 v[102:103], 9, v[102:103]
	v_lshlrev_b64 v[104:105], 9, v[104:105]
	v_lshl_add_u64 v[102:103], v[184:185], 0, v[102:103]
	v_lshl_add_u64 v[104:105], v[184:185], 0, v[104:105]
	global_load_dwordx2 v[158:159], v[102:103], off
	global_load_dwordx2 v[160:161], v[104:105], off
	global_load_dwordx2 v[156:157], v[104:105], off offset:256
	global_load_dwordx2 v[154:155], v[102:103], off offset:256
	s_waitcnt vmcnt(10)
	v_mfma_f32_32x32x16_bf16 v[0:15], v[28:31], v[90:93], v[0:15]
	v_or_b32_e32 v28, s17, v80
	v_ashrrev_i32_e32 v104, 2, v28
	v_cndmask_b32_e64 v28, v104, 0, s[36:37]
	v_ashrrev_i32_e32 v29, 31, v28
	v_readlane_b32 s40, v252, 5
	v_readlane_b32 s41, v252, 6
	v_readlane_b32 s42, v252, 7
	s_waitcnt vmcnt(8)
	v_mfma_f32_32x32x16_bf16 v[0:15], v[24:27], v[166:169], v[0:15]
	v_or_b32_e32 v26, 2, v104
	v_cndmask_b32_e64 v26, v26, 0, s[36:37]
	v_ashrrev_i32_e32 v27, 31, v26
	v_lshlrev_b64 v[24:25], 9, v[28:29]
	v_lshlrev_b64 v[26:27], 9, v[26:27]
	v_lshl_add_u64 v[24:25], v[184:185], 0, v[24:25]
	v_lshl_add_u64 v[26:27], v[184:185], 0, v[26:27]
	s_waitcnt vmcnt(8)
	v_mfma_f32_32x32x16_bf16 v[0:15], v[16:19], v[162:165], v[0:15]
	v_or_b32_e32 v16, 4, v104
	global_load_dwordx2 v[150:151], v[24:25], off
	global_load_dwordx2 v[152:153], v[26:27], off
	global_load_dwordx2 v[148:149], v[26:27], off offset:256
	global_load_dwordx2 v[146:147], v[24:25], off offset:256
	v_cndmask_b32_e64 v102, v16, 0, s[36:37]
	v_or_b32_e32 v104, 6, v104
	v_cndmask_b32_e64 v104, v104, 0, s[36:37]
	v_ashrrev_i32_e32 v103, 31, v102
	v_ashrrev_i32_e32 v105, 31, v104
	s_waitcnt vmcnt(12)
	v_mfma_f32_32x32x16_bf16 v[16:31], v[20:23], v[32:35], 0
	v_lshlrev_b64 v[102:103], 9, v[102:103]
	v_lshlrev_b64 v[104:105], 9, v[104:105]
	v_lshl_add_u64 v[102:103], v[184:185], 0, v[102:103]
	v_lshl_add_u64 v[104:105], v[184:185], 0, v[104:105]
	global_load_dwordx2 v[142:143], v[102:103], off
	global_load_dwordx2 v[144:145], v[104:105], off
	global_load_dwordx2 v[140:141], v[104:105], off offset:256
	global_load_dwordx2 v[138:139], v[102:103], off offset:256
	v_readlane_b32 s43, v252, 8
	s_waitcnt vmcnt(16)
	v_mfma_f32_32x32x16_bf16 v[16:31], v[76:79], v[90:93], v[16:31]
	v_or_b32_e32 v76, s16, v80
	v_ashrrev_i32_e32 v104, 2, v76
	v_cndmask_b32_e64 v76, v104, 0, s[8:9]
	v_ashrrev_i32_e32 v77, 31, v76
	s_waitcnt vmcnt(16)
	v_mfma_f32_32x32x16_bf16 v[16:31], v[72:75], v[166:169], v[16:31]
	v_or_b32_e32 v74, 2, v104
	v_cndmask_b32_e64 v74, v74, 0, s[8:9]
	v_ashrrev_i32_e32 v75, 31, v74
	v_lshlrev_b64 v[72:73], 9, v[76:77]
	v_lshlrev_b64 v[74:75], 9, v[74:75]
	v_lshl_add_u64 v[72:73], v[184:185], 0, v[72:73]
	s_waitcnt vmcnt(16)
	v_mfma_f32_32x32x16_bf16 v[16:31], v[64:67], v[162:165], v[16:31]
	v_lshl_add_u64 v[64:65], v[184:185], 0, v[74:75]
	global_load_dwordx2 v[134:135], v[72:73], off
	global_load_dwordx2 v[136:137], v[64:65], off
	global_load_dwordx2 v[132:133], v[64:65], off offset:256
	global_load_dwordx2 v[130:131], v[72:73], off offset:256
	v_or_b32_e32 v64, 4, v104
	v_cndmask_b32_e64 v102, v64, 0, s[8:9]
	v_or_b32_e32 v104, 6, v104
	v_cndmask_b32_e64 v104, v104, 0, s[8:9]
	v_ashrrev_i32_e32 v103, 31, v102
	s_waitcnt vmcnt(20)
	v_mfma_f32_32x32x16_bf16 v[64:79], v[68:71], v[32:35], 0
	v_ashrrev_i32_e32 v105, 31, v104
	v_lshlrev_b64 v[102:103], 9, v[102:103]
	v_lshlrev_b64 v[104:105], 9, v[104:105]
	v_lshl_add_u64 v[102:103], v[184:185], 0, v[102:103]
	s_waitcnt vmcnt(20)
	v_mfma_f32_32x32x16_bf16 v[64:79], v[60:63], v[90:93], v[64:79]
	v_lshl_add_u64 v[60:61], v[184:185], 0, v[104:105]
	global_load_dwordx2 v[126:127], v[102:103], off
	global_load_dwordx2 v[128:129], v[60:61], off
	global_load_dwordx2 v[124:125], v[60:61], off offset:256
	global_load_dwordx2 v[122:123], v[102:103], off offset:256
	v_or_b32_e32 v60, s15, v80
	v_ashrrev_i32_e32 v104, 2, v60
	v_or_b32_e32 v102, 4, v104
	v_cndmask_b32_e64 v102, v102, 0, s[4:5]
	v_ashrrev_i32_e32 v103, 31, v102
	s_waitcnt vmcnt(24)
; #define MFMA32(a, b, c) __builtin_amdgcn_mfma_f32_32x32x16_bf16((a), (b), (c), 0, 0, 0)
; __device__ __forceinline__ void attn_prompt_wave(const Params& P, int l, int qt, int tid_in) {
;     ...
;     f32x16 st[5];
; #pragma unroll
;     for (int kb = 0; kb < 5; ++kb) {
; #pragma unroll
;         for (int i = 0; i < 16; ++i) st[kb][i] = 0.f;
; #pragma unroll
;         for (int kk = 0; kk < 4; ++kk) st[kb] = MFMA32(kf[kb][kk], qf[kk], st[kb]);
;     }
;     const int qi = q0 + l32, bstart = (qi / LP) * LP;
;     const float sink = P.in[I_SINK][l * 8 + head];
;     float mx = sink;
;     const bool interior = key0 >= (q0 / LP) * LP && (q0 + 31) / LP == q0 / LP;
	v_mfma_f32_32x32x16_bf16 v[64:79], v[56:59], v[166:169], v[64:79]
	v_or_b32_e32 v58, 2, v104
	v_cndmask_b32_e64 v56, v104, 0, s[4:5]
	v_cndmask_b32_e64 v58, v58, 0, s[4:5]
	v_ashrrev_i32_e32 v57, 31, v56
	v_ashrrev_i32_e32 v59, 31, v58
	v_lshlrev_b64 v[56:57], 9, v[56:57]
	v_lshlrev_b64 v[58:59], 9, v[58:59]
	s_waitcnt vmcnt(24)
	v_mfma_f32_32x32x16_bf16 v[64:79], v[48:51], v[162:165], v[64:79]
	v_lshl_add_u64 v[48:49], v[184:185], 0, v[56:57]
	v_lshl_add_u64 v[50:51], v[184:185], 0, v[58:59]
	global_load_dwordx2 v[118:119], v[48:49], off
	global_load_dwordx2 v[120:121], v[50:51], off
	global_load_dwordx2 v[116:117], v[50:51], off offset:256
	global_load_dwordx2 v[114:115], v[48:49], off offset:256
	v_or_b32_e32 v104, 6, v104
	v_cndmask_b32_e64 v104, v104, 0, s[4:5]
	v_lshlrev_b64 v[102:103], 9, v[102:103]
	v_ashrrev_i32_e32 v105, 31, v104
	s_waitcnt vmcnt(28)
	v_mfma_f32_32x32x16_bf16 v[48:63], v[52:55], v[32:35], 0
	v_lshlrev_b64 v[104:105], 9, v[104:105]
	s_waitcnt vmcnt(28)
	v_mfma_f32_32x32x16_bf16 v[48:63], v[98:101], v[90:93], v[48:63]
	v_lshl_add_u64 v[98:99], v[184:185], 0, v[102:103]
	v_lshl_add_u64 v[100:101], v[184:185], 0, v[104:105]
	global_load_dwordx2 v[110:111], v[98:99], off
	global_load_dwordx2 v[112:113], v[100:101], off
	global_load_dwordx2 v[108:109], v[100:101], off offset:256
	global_load_dwordx2 v[106:107], v[98:99], off offset:256
	v_or_b32_e32 v98, s0, v80
	v_ashrrev_i32_e32 v188, 2, v98
	v_or_b32_e32 v186, 4, v188
	v_cndmask_b32_e64 v186, v186, 0, s[2:3]
	s_waitcnt vmcnt(32)
	v_mfma_f32_32x32x16_bf16 v[48:63], v[44:47], v[166:169], v[48:63]
	v_or_b32_e32 v46, 2, v188
	v_cndmask_b32_e64 v44, v188, 0, s[2:3]
	v_cndmask_b32_e64 v46, v46, 0, s[2:3]
	v_ashrrev_i32_e32 v45, 31, v44
	v_ashrrev_i32_e32 v47, 31, v46
	v_lshlrev_b64 v[44:45], 9, v[44:45]
	v_or_b32_e32 v188, 6, v188
	s_waitcnt vmcnt(32)
	v_mfma_f32_32x32x16_bf16 v[48:63], v[36:39], v[162:165], v[48:63]
	v_lshlrev_b64 v[36:37], 9, v[46:47]
	v_lshl_add_u64 v[38:39], v[184:185], 0, v[44:45]
	v_lshl_add_u64 v[36:37], v[184:185], 0, v[36:37]
	global_load_dwordx2 v[102:103], v[38:39], off
	global_load_dwordx2 v[104:105], v[36:37], off
	global_load_dwordx2 v[100:101], v[36:37], off offset:256
	global_load_dwordx2 v[98:99], v[38:39], off offset:256
	v_cndmask_b32_e64 v188, v188, 0, s[2:3]
	v_ashrrev_i32_e32 v187, 31, v186
	v_ashrrev_i32_e32 v189, 31, v188
	s_waitcnt vmcnt(36)
	v_mfma_f32_32x32x16_bf16 v[32:47], v[40:43], v[32:35], 0
	v_lshlrev_b64 v[186:187], 9, v[186:187]
	v_lshl_add_u64 v[186:187], v[184:185], 0, v[186:187]
	s_mul_hi_i32 s2, s0, 0xfe03f81
	s_lshr_b32 s3, s2, 31
	s_ashr_i32 s4, s2, 7
	s_add_i32 s4, s4, s3
	s_mul_i32 s2, s4, 0x810
	s_waitcnt vmcnt(36)
	v_mfma_f32_32x32x16_bf16 v[32:47], v[94:97], v[90:93], v[32:47]
	v_lshlrev_b64 v[90:91], 9, v[188:189]
	v_lshl_add_u64 v[90:91], v[184:185], 0, v[90:91]
	global_load_dwordx2 v[94:95], v[186:187], off
	global_load_dwordx2 v[96:97], v[90:91], off
	global_load_dwordx2 v[92:93], v[90:91], off offset:256
	s_nop 0
	global_load_dwordx2 v[90:91], v[186:187], off offset:256
	s_cmp_lt_i32 s1, s2
	s_mov_b64 s[2:3], 0
	s_waitcnt vmcnt(40)
	v_mfma_f32_32x32x16_bf16 v[32:47], v[174:177], v[166:169], v[32:47]
	v_add_u32_e32 v166, s13, v190
	v_ashrrev_i32_e32 v167, 31, v166
	v_lshl_add_u64 v[166:167], v[166:167], 2, s[54:55]
	global_load_dword v166, v[166:167], off
	s_waitcnt vmcnt(41)
	v_mfma_f32_32x32x16_bf16 v[32:47], v[170:173], v[162:165], v[32:47]
	s_cbranch_scc1 .LBB0_1022
	s_or_b32 s0, s0, 31
	s_mul_hi_i32 s0, s0, 0xfe03f81
	s_lshr_b32 s1, s0, 31
	s_ashr_i32 s0, s0, 7
	s_add_i32 s0, s0, s1
	s_cmp_eq_u32 s0, s4
	s_cselect_b64 s[2:3], -1, 0
